# v72 + the remaining 7 FF-OUT epilogue shuffle sites also converted to v_permlane16_swap (48 of 48 residual-epilogue reductions now without LDS round trips)
# baseline (speedup 1.0000x reference)
; __device__ __forceinline__ unsigned cvt_pk_bf16(float lo, float hi) { unsigned r; asm volatile("v_cvt_pk_bf16_f32 %0, %1, %2" : "=v"(r) : "v"(lo), "v"(hi)); return r; }
;     __device__ __forceinline__ void operator()(const f32x4 (&acc)[2][2][4][2], const Unit& u, int wr, int wc, int fr, int fq) const {
;     ...
;             for (int m = 0; m < 4; ++m) { const int row = row0 + ai * HALF + m * 16; const size_t off = (size_t)row * 1024 + col0; float s = 0.f;
; #pragma unroll
;                 for (int bj = 0; bj < 2; ++bj) { f32x4 b0, b1;
;                     if (base32) { b0 = *(const f32x4*)(base32 + off + bj * HALF); b1 = *(const f32x4*)(base32 + off + bj * HALF + 4); }
;                     else { const u32x4 hv = hv4[m][bj];
;                         b0 = (f32x4){__builtin_bit_cast(float, hv.x << 16), __builtin_bit_cast(float, hv.x & 0xffff0000u), __builtin_bit_cast(float, hv.y << 16), __builtin_bit_cast(float, hv.y & 0xffff0000u)};
;                         b1 = (f32x4){__builtin_bit_cast(float, hv.z << 16), __builtin_bit_cast(float, hv.z & 0xffff0000u), __builtin_bit_cast(float, hv.w << 16), __builtin_bit_cast(float, hv.w & 0xffff0000u)}; }
;                     const f32x4 o0 = b0 + acc[ai][bj][m][0], o1 = b1 + acc[ai][bj][m][1];
;                     s += ((o0[0] * o0[0] + o0[1] * o0[1]) + (o0[2] * o0[2] + o0[3] * o0[3])) + ((o1[0] * o1[0] + o1[1] * o1[1]) + (o1[2] * o1[2] + o1[3] * o1[3]));
;                     u32x4 w; w.x = cvt_pk_bf16(o0[0], o0[1]); w.y = cvt_pk_bf16(o0[2], o0[3]); w.z = cvt_pk_bf16(o1[0], o1[1]); w.w = cvt_pk_bf16(o1[2], o1[3]); *(u32x4*)(hb + off + bj * HALF) = w; }
;                 s += __shfl_xor(s, 16); s += __shfl_xor(s, 32);
;                 if (fq == 0) P[(wr * 64 + ai * HALF + m * 16 + fr) * 4 + wc] = s;
;                 asm volatile("" ::: "memory"); }
.LBB0_1365:
	s_or_b64 exec, exec, s[8:9]
	s_waitcnt lgkmcnt(0)
	v_lshlrev_b32_e32 v130, 16, v150
	v_and_b32_e32 v131, 0xffff0000, v150
	v_lshlrev_b32_e32 v132, 16, v151
	v_and_b32_e32 v133, 0xffff0000, v151
	v_lshlrev_b32_e32 v138, 16, v152
	v_and_b32_e32 v139, 0xffff0000, v152
	v_lshlrev_b32_e32 v140, 16, v153
	v_and_b32_e32 v141, 0xffff0000, v153
	v_pk_add_f32 v[112:113], v[112:113], v[132:133]
	v_pk_add_f32 v[110:111], v[110:111], v[130:131]
	v_pk_add_f32 v[130:131], v[108:109], v[140:141]
	v_pk_add_f32 v[108:109], v[106:107], v[138:139]
	v_mul_f32_e32 v106, v111, v111
	v_mul_f32_e32 v107, v113, v113
	v_fmac_f32_e32 v106, v110, v110
	v_fmac_f32_e32 v107, v112, v112
	v_add_f32_e32 v106, v106, v107
	v_mul_f32_e32 v107, v109, v109
	v_mul_f32_e32 v129, v131, v131
	v_fmac_f32_e32 v107, v108, v108
	v_fmac_f32_e32 v129, v130, v130
	v_add_f32_e32 v107, v107, v129
	v_add_f32_e32 v129, v106, v107
	v_cvt_pk_bf16_f32 v106, v110, v111
	v_cvt_pk_bf16_f32 v107, v112, v113
	v_lshlrev_b32_e32 v110, 16, v146
	v_and_b32_e32 v111, 0xffff0000, v146
	v_lshlrev_b32_e32 v112, 16, v147
	v_and_b32_e32 v113, 0xffff0000, v147
	v_cvt_pk_bf16_f32 v108, v108, v109
	v_cvt_pk_bf16_f32 v109, v130, v131
	v_lshlrev_b32_e32 v130, 16, v148
	v_and_b32_e32 v131, 0xffff0000, v148
	v_pk_add_f32 v[104:105], v[104:105], v[112:113]
	v_pk_add_f32 v[102:103], v[102:103], v[110:111]
	v_lshlrev_b32_e32 v132, 16, v149
	v_and_b32_e32 v133, 0xffff0000, v149
	v_pk_add_f32 v[112:113], v[98:99], v[130:131]
	v_mul_f32_e32 v98, v103, v103
	v_mul_f32_e32 v99, v105, v105
	v_pk_add_f32 v[110:111], v[100:101], v[132:133]
	v_fmac_f32_e32 v98, v102, v102
	v_fmac_f32_e32 v99, v104, v104
	v_add_f32_e32 v98, v98, v99
	v_mul_f32_e32 v99, v113, v113
	v_mul_f32_e32 v100, v111, v111
	v_fmac_f32_e32 v99, v112, v112
	v_fmac_f32_e32 v100, v110, v110
	v_add_f32_e32 v99, v99, v100
	v_add_f32_e32 v98, v98, v99
	v_add_f32_e32 v101, v129, v98
	v_mov_b32_e32 v206, v101
	v_mov_b32_e32 v207, v101
	s_nop 1
	v_permlane16_swap_b32 v206, v207
	s_nop 1
	v_lshl_add_u64 v[98:99], s[10:11], 0, v[182:183]
	v_lshl_add_u64 v[130:131], v[166:167], 1, v[98:99]
	global_store_dwordx4 v[130:131], v[106:109], off
	v_cvt_pk_bf16_f32 v100, v102, v103
	s_waitcnt lgkmcnt(0)
	v_add_f32_e32 v98, v206, v207
	v_mov_b32_e32 v99, v98
	s_nop 1
	v_permlane32_swap_b32 v98, v99
	s_nop 1
	v_cvt_pk_bf16_f32 v101, v104, v105
	v_cvt_pk_bf16_f32 v102, v112, v113
	v_cvt_pk_bf16_f32 v103, v110, v111
	global_store_dwordx4 v[130:131], v[100:103], off offset:256
	s_and_saveexec_b64 s[8:9], vcc
	s_cbranch_execz .LBB0_1367
	s_waitcnt lgkmcnt(0)
	v_add_f32_e32 v98, v98, v99
	ds_write_b32 v128, v98 offset:256
.LBB0_1367:
	s_or_b64 exec, exec, s[8:9]
	v_lshlrev_b32_e32 v98, 16, v134
	s_waitcnt lgkmcnt(0)
	v_and_b32_e32 v99, 0xffff0000, v134
	v_lshlrev_b32_e32 v100, 16, v135
	v_and_b32_e32 v101, 0xffff0000, v135
	v_lshlrev_b32_e32 v102, 16, v136
	v_and_b32_e32 v103, 0xffff0000, v136
	v_lshlrev_b32_e32 v104, 16, v137
	v_and_b32_e32 v105, 0xffff0000, v137
	v_pk_add_f32 v[96:97], v[96:97], v[100:101]
	v_pk_add_f32 v[94:95], v[94:95], v[98:99]
	v_pk_add_f32 v[98:99], v[92:93], v[104:105]
	v_pk_add_f32 v[92:93], v[90:91], v[102:103]
	v_mul_f32_e32 v90, v95, v95
	v_mul_f32_e32 v91, v97, v97
	v_fmac_f32_e32 v90, v94, v94
	v_fmac_f32_e32 v91, v96, v96
	v_add_f32_e32 v90, v90, v91
	v_mul_f32_e32 v91, v93, v93
	v_mul_f32_e32 v100, v99, v99
	v_fmac_f32_e32 v91, v92, v92
	v_fmac_f32_e32 v100, v98, v98
	v_add_f32_e32 v91, v91, v100
	v_add_f32_e32 v102, v90, v91
	v_cvt_pk_bf16_f32 v90, v94, v95
	v_cvt_pk_bf16_f32 v91, v96, v97
	v_lshlrev_b32_e32 v94, 16, v122
	v_and_b32_e32 v95, 0xffff0000, v122
	v_lshlrev_b32_e32 v96, 16, v123
	v_and_b32_e32 v97, 0xffff0000, v123
	v_cvt_pk_bf16_f32 v92, v92, v93
	v_cvt_pk_bf16_f32 v93, v98, v99
	v_lshlrev_b32_e32 v98, 16, v124
	v_and_b32_e32 v99, 0xffff0000, v124
	v_pk_add_f32 v[88:89], v[88:89], v[96:97]
	v_pk_add_f32 v[86:87], v[86:87], v[94:95]
	v_lshlrev_b32_e32 v100, 16, v125
	v_and_b32_e32 v101, 0xffff0000, v125
	v_pk_add_f32 v[96:97], v[82:83], v[98:99]
	v_mul_f32_e32 v82, v87, v87
	v_mul_f32_e32 v83, v89, v89
	v_pk_add_f32 v[94:95], v[84:85], v[100:101]
	v_fmac_f32_e32 v82, v86, v86
	v_fmac_f32_e32 v83, v88, v88
	v_add_f32_e32 v82, v82, v83
	v_mul_f32_e32 v83, v97, v97
	v_mul_f32_e32 v84, v95, v95
	v_fmac_f32_e32 v83, v96, v96
	v_fmac_f32_e32 v84, v94, v94
	v_add_f32_e32 v83, v83, v84
	v_add_f32_e32 v82, v82, v83
	v_add_f32_e32 v85, v102, v82
	v_mov_b32_e32 v206, v85
	v_mov_b32_e32 v207, v85
	s_nop 1
	v_permlane16_swap_b32 v206, v207
	s_nop 1
	v_lshl_add_u64 v[82:83], s[10:11], 0, v[180:181]
	v_lshl_add_u64 v[98:99], v[166:167], 1, v[82:83]
	global_store_dwordx4 v[98:99], v[90:93], off
	v_cvt_pk_bf16_f32 v84, v86, v87
	s_waitcnt lgkmcnt(0)
	v_add_f32_e32 v82, v206, v207
	v_mov_b32_e32 v83, v82
	s_nop 1
	v_permlane32_swap_b32 v82, v83
	s_nop 1
	v_cvt_pk_bf16_f32 v85, v88, v89
	v_cvt_pk_bf16_f32 v86, v96, v97
	v_cvt_pk_bf16_f32 v87, v94, v95
	global_store_dwordx4 v[98:99], v[84:87], off offset:256
	s_and_saveexec_b64 s[8:9], vcc
	s_cbranch_execz .LBB0_1369
	s_waitcnt lgkmcnt(0)
	v_add_f32_e32 v82, v82, v83
	ds_write_b32 v128, v82 offset:512
; __device__ __forceinline__ unsigned cvt_pk_bf16(float lo, float hi) { unsigned r; asm volatile("v_cvt_pk_bf16_f32 %0, %1, %2" : "=v"(r) : "v"(lo), "v"(hi)); return r; }
;     __device__ __forceinline__ void operator()(const f32x4 (&acc)[2][2][4][2], const Unit& u, int wr, int wc, int fr, int fq) const {
;     ...
;             u32x4 hv4[4][2];
;             if (!base32) {
; #pragma unroll
;                 for (int m = 0; m < 4; ++m)
; #pragma unroll
;                     for (int bj = 0; bj < 2; ++bj) hv4[m][bj] = *(const u32x4*)(hb + (size_t)(row0 + ai * HALF + m * 16) * 1024 + col0 + bj * HALF);
;             }
; #pragma unroll
;             for (int m = 0; m < 4; ++m) { const int row = row0 + ai * HALF + m * 16; const size_t off = (size_t)row * 1024 + col0; float s = 0.f;
; #pragma unroll
;                 for (int bj = 0; bj < 2; ++bj) { f32x4 b0, b1;
;                     if (base32) { b0 = *(const f32x4*)(base32 + off + bj * HALF); b1 = *(const f32x4*)(base32 + off + bj * HALF + 4); }
;                     else { const u32x4 hv = hv4[m][bj];
;                         b0 = (f32x4){__builtin_bit_cast(float, hv.x << 16), __builtin_bit_cast(float, hv.x & 0xffff0000u), __builtin_bit_cast(float, hv.y << 16), __builtin_bit_cast(float, hv.y & 0xffff0000u)};
;                         b1 = (f32x4){__builtin_bit_cast(float, hv.z << 16), __builtin_bit_cast(float, hv.z & 0xffff0000u), __builtin_bit_cast(float, hv.w << 16), __builtin_bit_cast(float, hv.w & 0xffff0000u)}; }
;                     const f32x4 o0 = b0 + acc[ai][bj][m][0], o1 = b1 + acc[ai][bj][m][1];
;                     s += ((o0[0] * o0[0] + o0[1] * o0[1]) + (o0[2] * o0[2] + o0[3] * o0[3])) + ((o1[0] * o1[0] + o1[1] * o1[1]) + (o1[2] * o1[2] + o1[3] * o1[3]));
;                     u32x4 w; w.x = cvt_pk_bf16(o0[0], o0[1]); w.y = cvt_pk_bf16(o0[2], o0[3]); w.z = cvt_pk_bf16(o1[0], o1[1]); w.w = cvt_pk_bf16(o1[2], o1[3]); *(u32x4*)(hb + off + bj * HALF) = w; }
;                 s += __shfl_xor(s, 16); s += __shfl_xor(s, 32);
;                 if (fq == 0) P[(wr * 64 + ai * HALF + m * 16 + fr) * 4 + wc] = s;
;                 asm volatile("" ::: "memory"); }
.LBB0_1369:
	s_or_b64 exec, exec, s[8:9]
	v_lshlrev_b32_e32 v82, 16, v118
	s_waitcnt lgkmcnt(0)
	v_and_b32_e32 v83, 0xffff0000, v118
	v_lshlrev_b32_e32 v84, 16, v119
	v_and_b32_e32 v85, 0xffff0000, v119
	v_lshlrev_b32_e32 v86, 16, v120
	v_and_b32_e32 v87, 0xffff0000, v120
	v_lshlrev_b32_e32 v88, 16, v121
	v_and_b32_e32 v89, 0xffff0000, v121
	v_pk_add_f32 v[80:81], v[80:81], v[84:85]
	v_pk_add_f32 v[78:79], v[78:79], v[82:83]
	v_pk_add_f32 v[82:83], v[76:77], v[88:89]
	v_pk_add_f32 v[76:77], v[74:75], v[86:87]
	v_mul_f32_e32 v74, v79, v79
	v_mul_f32_e32 v75, v81, v81
	v_fmac_f32_e32 v74, v78, v78
	v_fmac_f32_e32 v75, v80, v80
	v_add_f32_e32 v74, v74, v75
	v_mul_f32_e32 v75, v77, v77
	v_mul_f32_e32 v84, v83, v83
	v_fmac_f32_e32 v75, v76, v76
	v_fmac_f32_e32 v84, v82, v82
	v_add_f32_e32 v75, v75, v84
	v_add_f32_e32 v86, v74, v75
	v_cvt_pk_bf16_f32 v74, v78, v79
	v_cvt_pk_bf16_f32 v75, v80, v81
	v_lshlrev_b32_e32 v78, 16, v114
	v_and_b32_e32 v79, 0xffff0000, v114
	v_lshlrev_b32_e32 v80, 16, v115
	v_and_b32_e32 v81, 0xffff0000, v115
	v_cvt_pk_bf16_f32 v76, v76, v77
	v_cvt_pk_bf16_f32 v77, v82, v83
	v_lshlrev_b32_e32 v82, 16, v116
	v_and_b32_e32 v83, 0xffff0000, v116
	v_pk_add_f32 v[72:73], v[72:73], v[80:81]
	v_pk_add_f32 v[70:71], v[70:71], v[78:79]
	v_lshlrev_b32_e32 v84, 16, v117
	v_and_b32_e32 v85, 0xffff0000, v117
	v_pk_add_f32 v[80:81], v[66:67], v[82:83]
	v_mul_f32_e32 v66, v71, v71
	v_mul_f32_e32 v67, v73, v73
	v_pk_add_f32 v[78:79], v[68:69], v[84:85]
	v_fmac_f32_e32 v66, v70, v70
	v_fmac_f32_e32 v67, v72, v72
	v_add_f32_e32 v66, v66, v67
	v_mul_f32_e32 v67, v81, v81
	v_mul_f32_e32 v68, v79, v79
	v_fmac_f32_e32 v67, v80, v80
	v_fmac_f32_e32 v68, v78, v78
	v_add_f32_e32 v67, v67, v68
	v_add_f32_e32 v66, v66, v67
	v_add_f32_e32 v69, v86, v66
	v_mov_b32_e32 v206, v69
	v_mov_b32_e32 v207, v69
	s_nop 1
	v_permlane16_swap_b32 v206, v207
	s_nop 1
	v_lshl_add_u64 v[66:67], s[10:11], 0, v[172:173]
	v_lshl_add_u64 v[82:83], v[166:167], 1, v[66:67]
	global_store_dwordx4 v[82:83], v[74:77], off
	v_cvt_pk_bf16_f32 v68, v70, v71
	s_waitcnt lgkmcnt(0)
	v_add_f32_e32 v66, v206, v207
	v_mov_b32_e32 v67, v66
	s_nop 1
	v_permlane32_swap_b32 v66, v67
	s_nop 1
	v_cvt_pk_bf16_f32 v69, v72, v73
	v_cvt_pk_bf16_f32 v70, v80, v81
	v_cvt_pk_bf16_f32 v71, v78, v79
	global_store_dwordx4 v[82:83], v[68:71], off offset:256
	s_and_saveexec_b64 s[8:9], vcc
	s_cbranch_execz .LBB0_1371
	s_waitcnt lgkmcnt(0)
	v_add_f32_e32 v66, v66, v67
	ds_write_b32 v128, v66 offset:768
.LBB0_1371:
	s_or_b64 exec, exec, s[8:9]
	s_waitcnt lgkmcnt(0)
	v_lshlrev_b64 v[66:67], 11, v[170:171]
	s_mov_b64 s[8:9], 0x40000
	v_lshl_add_u64 v[104:105], v[66:67], 0, s[8:9]
	v_lshl_add_u64 v[68:69], v[168:169], 0, v[104:105]
	global_load_dwordx4 v[96:99], v[68:69], off
	global_load_dwordx4 v[100:103], v[68:69], off offset:256
	s_mov_b64 s[8:9], 0x48000
	v_lshl_add_u64 v[94:95], v[66:67], 0, s[8:9]
	s_mov_b64 s[8:9], 0x50000
	v_lshl_add_u64 v[92:93], v[66:67], 0, s[8:9]
	s_mov_b64 s[8:9], 0x58000
	v_lshl_add_u64 v[68:69], v[168:169], 0, v[94:95]
	v_lshl_add_u64 v[90:91], v[66:67], 0, s[8:9]
	global_load_dwordx4 v[86:89], v[68:69], off
	global_load_dwordx4 v[82:85], v[68:69], off offset:256
	v_lshl_add_u64 v[68:69], v[168:169], 0, v[92:93]
	v_lshl_add_u64 v[66:67], v[168:169], 0, v[90:91]
	global_load_dwordx4 v[78:81], v[68:69], off
	global_load_dwordx4 v[74:77], v[68:69], off offset:256
	global_load_dwordx4 v[70:73], v[66:67], off
	s_nop 0
	global_load_dwordx4 v[66:69], v[66:67], off offset:256
	s_waitcnt vmcnt(7)
	v_lshlrev_b32_e32 v106, 16, v96
	v_and_b32_e32 v107, 0xffff0000, v96
	v_lshlrev_b32_e32 v96, 16, v97
	v_and_b32_e32 v97, 0xffff0000, v97
	v_lshlrev_b32_e32 v108, 16, v98
	v_and_b32_e32 v109, 0xffff0000, v98
	v_lshlrev_b32_e32 v98, 16, v99
	v_and_b32_e32 v99, 0xffff0000, v99
	v_pk_add_f32 v[64:65], v[64:65], v[96:97]
	v_pk_add_f32 v[62:63], v[62:63], v[106:107]
	v_pk_add_f32 v[96:97], v[60:61], v[98:99]
	v_mul_f32_e32 v60, v63, v63
	v_mul_f32_e32 v61, v65, v65
	v_pk_add_f32 v[58:59], v[58:59], v[108:109]
	v_fmac_f32_e32 v60, v62, v62
	v_fmac_f32_e32 v61, v64, v64
	v_add_f32_e32 v60, v60, v61
	v_mul_f32_e32 v61, v59, v59
	v_mul_f32_e32 v98, v97, v97
	v_fmac_f32_e32 v61, v58, v58
	v_fmac_f32_e32 v98, v96, v96
	v_add_f32_e32 v61, v61, v98
	v_add_f32_e32 v98, v60, v61
	v_cvt_pk_bf16_f32 v60, v62, v63
	v_cvt_pk_bf16_f32 v61, v64, v65
	v_cvt_pk_bf16_f32 v62, v58, v59
	v_lshl_add_u64 v[58:59], s[10:11], 0, v[104:105]
	v_cvt_pk_bf16_f32 v63, v96, v97
	v_lshl_add_u64 v[58:59], v[166:167], 1, v[58:59]
	global_store_dwordx4 v[58:59], v[60:63], off
	s_waitcnt vmcnt(7)
	v_lshlrev_b32_e32 v64, 16, v102
	v_and_b32_e32 v65, 0xffff0000, v102
	v_lshlrev_b32_e32 v60, 16, v100
	v_and_b32_e32 v61, 0xffff0000, v100
	v_lshlrev_b32_e32 v62, 16, v101
	v_and_b32_e32 v63, 0xffff0000, v101
	v_lshlrev_b32_e32 v96, 16, v103
	v_and_b32_e32 v97, 0xffff0000, v103
	v_pk_add_f32 v[56:57], v[56:57], v[62:63]
	v_pk_add_f32 v[54:55], v[54:55], v[60:61]
	v_pk_add_f32 v[60:61], v[52:53], v[96:97]
	v_pk_add_f32 v[52:53], v[50:51], v[64:65]
	v_mul_f32_e32 v50, v55, v55
	v_mul_f32_e32 v51, v57, v57
	v_fmac_f32_e32 v50, v54, v54
	v_fmac_f32_e32 v51, v56, v56
	v_add_f32_e32 v50, v50, v51
	v_mul_f32_e32 v51, v53, v53
	v_mul_f32_e32 v62, v61, v61
	v_fmac_f32_e32 v51, v52, v52
	v_fmac_f32_e32 v62, v60, v60
	v_add_f32_e32 v51, v51, v62
	v_add_f32_e32 v50, v50, v51
	v_add_f32_e32 v62, v98, v50
	v_cvt_pk_bf16_f32 v50, v54, v55
	v_cvt_pk_bf16_f32 v51, v56, v57
	v_cvt_pk_bf16_f32 v52, v52, v53
	v_cvt_pk_bf16_f32 v53, v60, v61
	global_store_dwordx4 v[58:59], v[50:53], off offset:256
	v_mov_b32_e32 v206, v62
	v_mov_b32_e32 v207, v62
	s_nop 1
	v_permlane16_swap_b32 v206, v207
	s_nop 1
	s_waitcnt lgkmcnt(0)
	v_add_f32_e32 v50, v206, v207
	v_mov_b32_e32 v51, v50
	s_nop 1
	v_permlane32_swap_b32 v50, v51
	s_nop 1
	s_and_saveexec_b64 s[8:9], vcc
	s_cbranch_execz .LBB0_1373
	s_waitcnt lgkmcnt(0)
	v_add_f32_e32 v50, v50, v51
	ds_write_b32 v128, v50 offset:2048
; __device__ __forceinline__ unsigned cvt_pk_bf16(float lo, float hi) { unsigned r; asm volatile("v_cvt_pk_bf16_f32 %0, %1, %2" : "=v"(r) : "v"(lo), "v"(hi)); return r; }
;     __device__ __forceinline__ void operator()(const f32x4 (&acc)[2][2][4][2], const Unit& u, int wr, int wc, int fr, int fq) const {
;     ...
;             for (int m = 0; m < 4; ++m) { const int row = row0 + ai * HALF + m * 16; const size_t off = (size_t)row * 1024 + col0; float s = 0.f;
; #pragma unroll
;                 for (int bj = 0; bj < 2; ++bj) { f32x4 b0, b1;
;                     if (base32) { b0 = *(const f32x4*)(base32 + off + bj * HALF); b1 = *(const f32x4*)(base32 + off + bj * HALF + 4); }
;                     else { const u32x4 hv = hv4[m][bj];
;                         b0 = (f32x4){__builtin_bit_cast(float, hv.x << 16), __builtin_bit_cast(float, hv.x & 0xffff0000u), __builtin_bit_cast(float, hv.y << 16), __builtin_bit_cast(float, hv.y & 0xffff0000u)};
;                         b1 = (f32x4){__builtin_bit_cast(float, hv.z << 16), __builtin_bit_cast(float, hv.z & 0xffff0000u), __builtin_bit_cast(float, hv.w << 16), __builtin_bit_cast(float, hv.w & 0xffff0000u)}; }
;                     const f32x4 o0 = b0 + acc[ai][bj][m][0], o1 = b1 + acc[ai][bj][m][1];
;                     s += ((o0[0] * o0[0] + o0[1] * o0[1]) + (o0[2] * o0[2] + o0[3] * o0[3])) + ((o1[0] * o1[0] + o1[1] * o1[1]) + (o1[2] * o1[2] + o1[3] * o1[3]));
;                     u32x4 w; w.x = cvt_pk_bf16(o0[0], o0[1]); w.y = cvt_pk_bf16(o0[2], o0[3]); w.z = cvt_pk_bf16(o1[0], o1[1]); w.w = cvt_pk_bf16(o1[2], o1[3]); *(u32x4*)(hb + off + bj * HALF) = w; }
;                 s += __shfl_xor(s, 16); s += __shfl_xor(s, 32);
;                 if (fq == 0) P[(wr * 64 + ai * HALF + m * 16 + fr) * 4 + wc] = s;
;                 asm volatile("" ::: "memory"); }
.LBB0_1373:
	s_or_b64 exec, exec, s[8:9]
	s_waitcnt vmcnt(7)
	v_lshlrev_b32_e32 v50, 16, v86
	s_waitcnt lgkmcnt(0)
	v_and_b32_e32 v51, 0xffff0000, v86
	v_lshlrev_b32_e32 v52, 16, v87
	v_and_b32_e32 v53, 0xffff0000, v87
	v_lshlrev_b32_e32 v54, 16, v88
	v_and_b32_e32 v55, 0xffff0000, v88
	v_lshlrev_b32_e32 v56, 16, v89
	v_and_b32_e32 v57, 0xffff0000, v89
	v_pk_add_f32 v[48:49], v[48:49], v[52:53]
	v_pk_add_f32 v[46:47], v[46:47], v[50:51]
	v_pk_add_f32 v[50:51], v[44:45], v[56:57]
	v_pk_add_f32 v[44:45], v[42:43], v[54:55]
	v_mul_f32_e32 v42, v47, v47
	v_mul_f32_e32 v43, v49, v49
	v_fmac_f32_e32 v42, v46, v46
	v_fmac_f32_e32 v43, v48, v48
	v_add_f32_e32 v42, v42, v43
	v_mul_f32_e32 v43, v45, v45
	v_mul_f32_e32 v52, v51, v51
	v_fmac_f32_e32 v43, v44, v44
	v_fmac_f32_e32 v52, v50, v50
	v_add_f32_e32 v43, v43, v52
	v_add_f32_e32 v54, v42, v43
	v_cvt_pk_bf16_f32 v42, v46, v47
	v_cvt_pk_bf16_f32 v43, v48, v49
	s_waitcnt vmcnt(6)
	v_lshlrev_b32_e32 v46, 16, v82
	v_and_b32_e32 v47, 0xffff0000, v82
	v_lshlrev_b32_e32 v48, 16, v83
	v_and_b32_e32 v49, 0xffff0000, v83
	v_cvt_pk_bf16_f32 v44, v44, v45
	v_cvt_pk_bf16_f32 v45, v50, v51
	v_lshlrev_b32_e32 v50, 16, v84
	v_and_b32_e32 v51, 0xffff0000, v84
	v_pk_add_f32 v[40:41], v[40:41], v[48:49]
	v_pk_add_f32 v[38:39], v[38:39], v[46:47]
	v_lshlrev_b32_e32 v52, 16, v85
	v_and_b32_e32 v53, 0xffff0000, v85
	v_pk_add_f32 v[48:49], v[34:35], v[50:51]
	v_mul_f32_e32 v34, v39, v39
	v_mul_f32_e32 v35, v41, v41
	v_pk_add_f32 v[46:47], v[36:37], v[52:53]
	v_fmac_f32_e32 v34, v38, v38
	v_fmac_f32_e32 v35, v40, v40
	v_add_f32_e32 v34, v34, v35
	v_mul_f32_e32 v35, v49, v49
	v_mul_f32_e32 v36, v47, v47
	v_fmac_f32_e32 v35, v48, v48
	v_fmac_f32_e32 v36, v46, v46
	v_add_f32_e32 v35, v35, v36
	v_add_f32_e32 v34, v34, v35
	v_add_f32_e32 v37, v54, v34
	v_mov_b32_e32 v206, v37
	v_mov_b32_e32 v207, v37
	s_nop 1
	v_permlane16_swap_b32 v206, v207
	s_nop 1
	v_lshl_add_u64 v[34:35], s[10:11], 0, v[94:95]
	v_lshl_add_u64 v[50:51], v[166:167], 1, v[34:35]
	global_store_dwordx4 v[50:51], v[42:45], off
	v_cvt_pk_bf16_f32 v36, v38, v39
	s_waitcnt lgkmcnt(0)
	v_add_f32_e32 v34, v206, v207
	v_mov_b32_e32 v35, v34
	s_nop 1
	v_permlane32_swap_b32 v34, v35
	s_nop 1
	v_cvt_pk_bf16_f32 v37, v40, v41
	v_cvt_pk_bf16_f32 v38, v48, v49
	v_cvt_pk_bf16_f32 v39, v46, v47
	global_store_dwordx4 v[50:51], v[36:39], off offset:256
	s_and_saveexec_b64 s[8:9], vcc
	s_cbranch_execz .LBB0_1375
	s_waitcnt lgkmcnt(0)
	v_add_f32_e32 v34, v34, v35
	ds_write_b32 v128, v34 offset:2304
; __device__ __forceinline__ unsigned cvt_pk_bf16(float lo, float hi) { unsigned r; asm volatile("v_cvt_pk_bf16_f32 %0, %1, %2" : "=v"(r) : "v"(lo), "v"(hi)); return r; }
;     __device__ __forceinline__ void operator()(const f32x4 (&acc)[2][2][4][2], const Unit& u, int wr, int wc, int fr, int fq) const {
;     ...
;             for (int m = 0; m < 4; ++m) { const int row = row0 + ai * HALF + m * 16; const size_t off = (size_t)row * 1024 + col0; float s = 0.f;
; #pragma unroll
;                 for (int bj = 0; bj < 2; ++bj) { f32x4 b0, b1;
;                     if (base32) { b0 = *(const f32x4*)(base32 + off + bj * HALF); b1 = *(const f32x4*)(base32 + off + bj * HALF + 4); }
;                     else { const u32x4 hv = hv4[m][bj];
;                         b0 = (f32x4){__builtin_bit_cast(float, hv.x << 16), __builtin_bit_cast(float, hv.x & 0xffff0000u), __builtin_bit_cast(float, hv.y << 16), __builtin_bit_cast(float, hv.y & 0xffff0000u)};
;                         b1 = (f32x4){__builtin_bit_cast(float, hv.z << 16), __builtin_bit_cast(float, hv.z & 0xffff0000u), __builtin_bit_cast(float, hv.w << 16), __builtin_bit_cast(float, hv.w & 0xffff0000u)}; }
;                     const f32x4 o0 = b0 + acc[ai][bj][m][0], o1 = b1 + acc[ai][bj][m][1];
;                     s += ((o0[0] * o0[0] + o0[1] * o0[1]) + (o0[2] * o0[2] + o0[3] * o0[3])) + ((o1[0] * o1[0] + o1[1] * o1[1]) + (o1[2] * o1[2] + o1[3] * o1[3]));
;                     u32x4 w; w.x = cvt_pk_bf16(o0[0], o0[1]); w.y = cvt_pk_bf16(o0[2], o0[3]); w.z = cvt_pk_bf16(o1[0], o1[1]); w.w = cvt_pk_bf16(o1[2], o1[3]); *(u32x4*)(hb + off + bj * HALF) = w; }
;                 s += __shfl_xor(s, 16); s += __shfl_xor(s, 32);
;                 if (fq == 0) P[(wr * 64 + ai * HALF + m * 16 + fr) * 4 + wc] = s;
;                 asm volatile("" ::: "memory"); }
.LBB0_1375:
	s_or_b64 exec, exec, s[8:9]
	s_waitcnt vmcnt(7)
	v_lshlrev_b32_e32 v34, 16, v78
	s_waitcnt lgkmcnt(0)
	v_and_b32_e32 v35, 0xffff0000, v78
	v_lshlrev_b32_e32 v36, 16, v79
	v_and_b32_e32 v37, 0xffff0000, v79
	v_lshlrev_b32_e32 v38, 16, v80
	v_and_b32_e32 v39, 0xffff0000, v80
	v_lshlrev_b32_e32 v40, 16, v81
	v_and_b32_e32 v41, 0xffff0000, v81
	v_pk_add_f32 v[32:33], v[32:33], v[36:37]
	v_pk_add_f32 v[30:31], v[30:31], v[34:35]
	v_pk_add_f32 v[34:35], v[28:29], v[40:41]
	v_pk_add_f32 v[28:29], v[26:27], v[38:39]
	v_mul_f32_e32 v26, v31, v31
	v_mul_f32_e32 v27, v33, v33
	v_fmac_f32_e32 v26, v30, v30
	v_fmac_f32_e32 v27, v32, v32
	v_add_f32_e32 v26, v26, v27
	v_mul_f32_e32 v27, v29, v29
	v_mul_f32_e32 v36, v35, v35
	v_fmac_f32_e32 v27, v28, v28
	v_fmac_f32_e32 v36, v34, v34
	v_add_f32_e32 v27, v27, v36
	v_add_f32_e32 v38, v26, v27
	v_cvt_pk_bf16_f32 v26, v30, v31
	v_cvt_pk_bf16_f32 v27, v32, v33
	s_waitcnt vmcnt(6)
	v_lshlrev_b32_e32 v30, 16, v74
	v_and_b32_e32 v31, 0xffff0000, v74
	v_lshlrev_b32_e32 v32, 16, v75
	v_and_b32_e32 v33, 0xffff0000, v75
	v_cvt_pk_bf16_f32 v28, v28, v29
	v_cvt_pk_bf16_f32 v29, v34, v35
	v_lshlrev_b32_e32 v34, 16, v76
	v_and_b32_e32 v35, 0xffff0000, v76
	v_pk_add_f32 v[24:25], v[24:25], v[32:33]
	v_pk_add_f32 v[22:23], v[22:23], v[30:31]
	v_lshlrev_b32_e32 v36, 16, v77
	v_and_b32_e32 v37, 0xffff0000, v77
	v_pk_add_f32 v[32:33], v[18:19], v[34:35]
	v_mul_f32_e32 v18, v23, v23
	v_mul_f32_e32 v19, v25, v25
	v_pk_add_f32 v[30:31], v[20:21], v[36:37]
	v_fmac_f32_e32 v18, v22, v22
	v_fmac_f32_e32 v19, v24, v24
	v_add_f32_e32 v18, v18, v19
	v_mul_f32_e32 v19, v33, v33
	v_mul_f32_e32 v20, v31, v31
	v_fmac_f32_e32 v19, v32, v32
	v_fmac_f32_e32 v20, v30, v30
	v_add_f32_e32 v19, v19, v20
	v_add_f32_e32 v18, v18, v19
	v_add_f32_e32 v21, v38, v18
	v_mov_b32_e32 v206, v21
	v_mov_b32_e32 v207, v21
	s_nop 1
	v_permlane16_swap_b32 v206, v207
	s_nop 1
	v_lshl_add_u64 v[18:19], s[10:11], 0, v[92:93]
	v_lshl_add_u64 v[34:35], v[166:167], 1, v[18:19]
	global_store_dwordx4 v[34:35], v[26:29], off
	v_cvt_pk_bf16_f32 v20, v22, v23
	s_waitcnt lgkmcnt(0)
	v_add_f32_e32 v18, v206, v207
	v_mov_b32_e32 v19, v18
	s_nop 1
	v_permlane32_swap_b32 v18, v19
	s_nop 1
	v_cvt_pk_bf16_f32 v21, v24, v25
	v_cvt_pk_bf16_f32 v22, v32, v33
	v_cvt_pk_bf16_f32 v23, v30, v31
	global_store_dwordx4 v[34:35], v[20:23], off offset:256
	s_and_saveexec_b64 s[8:9], vcc
	s_cbranch_execz .LBB0_1377
	s_waitcnt lgkmcnt(0)
	v_add_f32_e32 v18, v18, v19
	ds_write_b32 v128, v18 offset:2560
.LBB0_1377:
	s_or_b64 exec, exec, s[8:9]
	s_waitcnt vmcnt(7)
	v_lshlrev_b32_e32 v18, 16, v70
	s_waitcnt lgkmcnt(0)
	v_and_b32_e32 v19, 0xffff0000, v70
	v_lshlrev_b32_e32 v20, 16, v71
	v_and_b32_e32 v21, 0xffff0000, v71
	v_lshlrev_b32_e32 v22, 16, v72
	v_and_b32_e32 v23, 0xffff0000, v72
	v_lshlrev_b32_e32 v24, 16, v73
	v_and_b32_e32 v25, 0xffff0000, v73
	v_pk_add_f32 v[16:17], v[16:17], v[20:21]
	v_pk_add_f32 v[14:15], v[14:15], v[18:19]
	v_pk_add_f32 v[18:19], v[12:13], v[24:25]
	v_pk_add_f32 v[12:13], v[10:11], v[22:23]
	v_mul_f32_e32 v10, v15, v15
	v_mul_f32_e32 v11, v17, v17
	v_fmac_f32_e32 v10, v14, v14
	v_fmac_f32_e32 v11, v16, v16
	v_add_f32_e32 v10, v10, v11
	v_mul_f32_e32 v11, v13, v13
	v_mul_f32_e32 v20, v19, v19
	v_fmac_f32_e32 v11, v12, v12
	v_fmac_f32_e32 v20, v18, v18
	v_add_f32_e32 v11, v11, v20
	v_add_f32_e32 v22, v10, v11
	v_cvt_pk_bf16_f32 v10, v14, v15
	v_cvt_pk_bf16_f32 v11, v16, v17
	s_waitcnt vmcnt(6)
	v_lshlrev_b32_e32 v14, 16, v66
	v_and_b32_e32 v15, 0xffff0000, v66
	v_lshlrev_b32_e32 v16, 16, v67
	v_and_b32_e32 v17, 0xffff0000, v67
	v_cvt_pk_bf16_f32 v12, v12, v13
	v_cvt_pk_bf16_f32 v13, v18, v19
	v_lshlrev_b32_e32 v18, 16, v68
	v_and_b32_e32 v19, 0xffff0000, v68
	v_pk_add_f32 v[8:9], v[8:9], v[16:17]
	v_pk_add_f32 v[6:7], v[6:7], v[14:15]
	v_lshlrev_b32_e32 v20, 16, v69
	v_and_b32_e32 v21, 0xffff0000, v69
	v_pk_add_f32 v[16:17], v[2:3], v[18:19]
	v_mul_f32_e32 v2, v7, v7
	v_mul_f32_e32 v3, v9, v9
	v_pk_add_f32 v[14:15], v[4:5], v[20:21]
	v_fmac_f32_e32 v2, v6, v6
	v_fmac_f32_e32 v3, v8, v8
	v_add_f32_e32 v2, v2, v3
	v_mul_f32_e32 v3, v17, v17
	v_mul_f32_e32 v4, v15, v15
	v_fmac_f32_e32 v3, v16, v16
	v_fmac_f32_e32 v4, v14, v14
	v_add_f32_e32 v3, v3, v4
	v_add_f32_e32 v2, v2, v3
	v_add_f32_e32 v5, v22, v2
	v_mov_b32_e32 v206, v5
	v_mov_b32_e32 v207, v5
	s_nop 1
	v_permlane16_swap_b32 v206, v207
	s_nop 1
	v_lshl_add_u64 v[2:3], s[10:11], 0, v[90:91]
	v_lshl_add_u64 v[18:19], v[166:167], 1, v[2:3]
	global_store_dwordx4 v[18:19], v[10:13], off
	v_cvt_pk_bf16_f32 v4, v6, v7
	s_waitcnt lgkmcnt(0)
	v_add_f32_e32 v2, v206, v207
	v_mov_b32_e32 v3, v2
	s_nop 1
	v_permlane32_swap_b32 v2, v3
	s_nop 1
	v_cvt_pk_bf16_f32 v5, v8, v9
	v_cvt_pk_bf16_f32 v6, v16, v17
	v_cvt_pk_bf16_f32 v7, v14, v15
	global_store_dwordx4 v[18:19], v[4:7], off offset:256
	s_and_saveexec_b64 s[8:9], vcc
	s_cbranch_execz .LBB0_1379
	s_waitcnt lgkmcnt(0)
	v_add_f32_e32 v2, v2, v3
	ds_write_b32 v128, v2 offset:2816
